# modnorm passes (phases 1/7/10/17): non-temporal policy also on the bf16 output stores
# speedup vs baseline: 1.0024x; 1.0024x over previous
; DEV unsigned cvt_pk_bf16(float lo, float hi) { unsigned r; asm volatile("v_cvt_pk_bf16_f32 %0, %1, %2" : "=v"(r) : "v"(lo), "v"(hi)); return r; }
; DEV void modnorm_rows(const float* srcX, const float* srcC, int nrows, const float* g, const float* shift, const float* scale, bf16_t* dst, int gw, int NGW, int lane) {
;     for (int row0 = gw; row0 < nrows; row0 += 2 * NGW) {
;         const int row1 = row0 + NGW; const bool has1 = row1 < nrows;
;     ...
;         for (int j = 0; j < 4; ++j) { const int col = 256 * j + 4 * lane; const f32x4 gg = *(const f32x4*)(g + col);
;             { const f32x4 sh = *(const f32x4*)(shift + (size_t)mr0 * 6144 + col), sc = *(const f32x4*)(scale + (size_t)mr0 * 6144 + col); f32x4 y;
; #pragma unroll
;                 for (int e = 0; e < 4; ++e) y[e] = (v0[j][e] * rstd0 * gg[e]) * (1.f + sc[e]) + sh[e];
;                 u32x2 w; w.x = cvt_pk_bf16(y[0], y[1]); w.y = cvt_pk_bf16(y[2], y[3]); *(u32x2*)(dst + (size_t)row0 * DM + col) = w; }
;             if (has1) { const f32x4 sh = *(const f32x4*)(shift + (size_t)mr1 * 6144 + col), sc = *(const f32x4*)(scale + (size_t)mr1 * 6144 + col); f32x4 y;
; #pragma unroll
;                 for (int e = 0; e < 4; ++e) y[e] = (v1[j][e] * rstd1 * gg[e]) * (1.f + sc[e]) + sh[e];
;                 u32x2 w; w.x = cvt_pk_bf16(y[0], y[1]); w.y = cvt_pk_bf16(y[2], y[3]); *(u32x2*)(dst + (size_t)row1 * DM + col) = w; } }
.Lmn7_ni_6:
	s_add_u32 s14, s14, s1
	global_store_dwordx2 v123, v[114:115], s[22:23] offset:0 nt
	global_store_dwordx2 v123, v[116:117], s[22:23] offset:512 nt
	global_store_dwordx2 v123, v[118:119], s[22:23] offset:1024 nt
	global_store_dwordx2 v123, v[120:121], s[22:23] offset:1536 nt
	s_add_u32 s15, s15, s1
	s_cmp_ge_i32 s15, 0x8800
	s_cbranch_scc1 .Lmn7_done_1
	s_add_u32 s20, s15, s1
	s_cmp_ge_i32 s20, 0x8800
	s_cbranch_scc1 .Lmn7_wl_7
	s_waitcnt vmcnt(16)
	s_branch .Lmn7_wj_8

; DEV unsigned cvt_pk_bf16(float lo, float hi) { unsigned r; asm volatile("v_cvt_pk_bf16_f32 %0, %1, %2" : "=v"(r) : "v"(lo), "v"(hi)); return r; }
; DEV void modnorm_rows(const float* srcX, const float* srcC, int nrows, const float* g, const float* shift, const float* scale, bf16_t* dst, int gw, int NGW, int lane) {
;     ...
;         for (int j = 0; j < 4; ++j) { const int col = 256 * j + 4 * lane; const f32x4 gg = *(const f32x4*)(g + col);
;             { const f32x4 sh = *(const f32x4*)(shift + (size_t)mr0 * 6144 + col), sc = *(const f32x4*)(scale + (size_t)mr0 * 6144 + col); f32x4 y;
; #pragma unroll
;                 for (int e = 0; e < 4; ++e) y[e] = (v0[j][e] * rstd0 * gg[e]) * (1.f + sc[e]) + sh[e];
;                 u32x2 w; w.x = cvt_pk_bf16(y[0], y[1]); w.y = cvt_pk_bf16(y[2], y[3]); *(u32x2*)(dst + (size_t)row0 * DM + col) = w; }
;             if (has1) { const f32x4 sh = *(const f32x4*)(shift + (size_t)mr1 * 6144 + col), sc = *(const f32x4*)(scale + (size_t)mr1 * 6144 + col); f32x4 y;
; #pragma unroll
;                 for (int e = 0; e < 4; ++e) y[e] = (v1[j][e] * rstd1 * gg[e]) * (1.f + sc[e]) + sh[e];
;                 u32x2 w; w.x = cvt_pk_bf16(y[0], y[1]); w.y = cvt_pk_bf16(y[2], y[3]); *(u32x2*)(dst + (size_t)row1 * DM + col) = w; } }
.Lmn7_ni_9:
	s_add_u32 s14, s14, s1
	global_store_dwordx2 v123, v[114:115], s[22:23] offset:0 nt
	global_store_dwordx2 v123, v[116:117], s[22:23] offset:512 nt
	global_store_dwordx2 v123, v[118:119], s[22:23] offset:1024 nt
	global_store_dwordx2 v123, v[120:121], s[22:23] offset:1536 nt
	s_add_u32 s15, s15, s1

; DEV unsigned cvt_pk_bf16(float lo, float hi) { unsigned r; asm volatile("v_cvt_pk_bf16_f32 %0, %1, %2" : "=v"(r) : "v"(lo), "v"(hi)); return r; }
; DEV void modnorm_rows(const float* srcX, const float* srcC, int nrows, const float* g, const float* shift, const float* scale, bf16_t* dst, int gw, int NGW, int lane) {
;     ...
;         for (int j = 0; j < 4; ++j) { const int col = 256 * j + 4 * lane; const f32x4 gg = *(const f32x4*)(g + col);
;             { const f32x4 sh = *(const f32x4*)(shift + (size_t)mr0 * 6144 + col), sc = *(const f32x4*)(scale + (size_t)mr0 * 6144 + col); f32x4 y;
; #pragma unroll
;                 for (int e = 0; e < 4; ++e) y[e] = (v0[j][e] * rstd0 * gg[e]) * (1.f + sc[e]) + sh[e];
;                 u32x2 w; w.x = cvt_pk_bf16(y[0], y[1]); w.y = cvt_pk_bf16(y[2], y[3]); *(u32x2*)(dst + (size_t)row0 * DM + col) = w; }
;             if (has1) { const f32x4 sh = *(const f32x4*)(shift + (size_t)mr1 * 6144 + col), sc = *(const f32x4*)(scale + (size_t)mr1 * 6144 + col); f32x4 y;
; #pragma unroll
;                 for (int e = 0; e < 4; ++e) y[e] = (v1[j][e] * rstd1 * gg[e]) * (1.f + sc[e]) + sh[e];
;                 u32x2 w; w.x = cvt_pk_bf16(y[0], y[1]); w.y = cvt_pk_bf16(y[2], y[3]); *(u32x2*)(dst + (size_t)row1 * DM + col) = w; } }
.Lmn7_ni_13:
	s_add_u32 s14, s14, s1
	global_store_dwordx2 v123, v[114:115], s[22:23] offset:0 nt
	global_store_dwordx2 v123, v[116:117], s[22:23] offset:512 nt
	global_store_dwordx2 v123, v[118:119], s[22:23] offset:1024 nt
	global_store_dwordx2 v123, v[120:121], s[22:23] offset:1536 nt
	s_add_u32 s15, s15, s1
	s_cmp_ge_i32 s15, 0x8800
	s_cbranch_scc1 .Lmn7_done_1
	s_add_u32 s20, s15, s1
	s_cmp_ge_i32 s20, 0x8800
	s_cbranch_scc1 .Lmn7_wl_14
	s_waitcnt vmcnt(20)
	s_branch .Lmn7_wj_15

; DEV unsigned cvt_pk_bf16(float lo, float hi) { unsigned r; asm volatile("v_cvt_pk_bf16_f32 %0, %1, %2" : "=v"(r) : "v"(lo), "v"(hi)); return r; }
; DEV void modnorm_rows(const float* srcX, const float* srcC, int nrows, const float* g, const float* shift, const float* scale, bf16_t* dst, int gw, int NGW, int lane) {
;     ...
;         for (int j = 0; j < 4; ++j) { const int col = 256 * j + 4 * lane; const f32x4 gg = *(const f32x4*)(g + col);
;             { const f32x4 sh = *(const f32x4*)(shift + (size_t)mr0 * 6144 + col), sc = *(const f32x4*)(scale + (size_t)mr0 * 6144 + col); f32x4 y;
; #pragma unroll
;                 for (int e = 0; e < 4; ++e) y[e] = (v0[j][e] * rstd0 * gg[e]) * (1.f + sc[e]) + sh[e];
;                 u32x2 w; w.x = cvt_pk_bf16(y[0], y[1]); w.y = cvt_pk_bf16(y[2], y[3]); *(u32x2*)(dst + (size_t)row0 * DM + col) = w; }
;             if (has1) { const f32x4 sh = *(const f32x4*)(shift + (size_t)mr1 * 6144 + col), sc = *(const f32x4*)(scale + (size_t)mr1 * 6144 + col); f32x4 y;
; #pragma unroll
;                 for (int e = 0; e < 4; ++e) y[e] = (v1[j][e] * rstd1 * gg[e]) * (1.f + sc[e]) + sh[e];
;                 u32x2 w; w.x = cvt_pk_bf16(y[0], y[1]); w.y = cvt_pk_bf16(y[2], y[3]); *(u32x2*)(dst + (size_t)row1 * DM + col) = w; } }
.Lmn7_ni_16:
	s_add_u32 s14, s14, s1
	global_store_dwordx2 v123, v[114:115], s[22:23] offset:0 nt
	global_store_dwordx2 v123, v[116:117], s[22:23] offset:512 nt
	global_store_dwordx2 v123, v[118:119], s[22:23] offset:1024 nt
	global_store_dwordx2 v123, v[120:121], s[22:23] offset:1536 nt
	s_add_u32 s15, s15, s1
	s_branch .Lmn7_loop_10

; DEV unsigned cvt_pk_bf16(float lo, float hi) { unsigned r; asm volatile("v_cvt_pk_bf16_f32 %0, %1, %2" : "=v"(r) : "v"(lo), "v"(hi)); return r; }
; DEV void modnorm_rows(const float* srcX, const float* srcC, int nrows, const float* g, const float* shift, const float* scale, bf16_t* dst, int gw, int NGW, int lane) {
;     ...
;         for (int j = 0; j < 4; ++j) { const int col = 256 * j + 4 * lane; const f32x4 gg = *(const f32x4*)(g + col);
;             { const f32x4 sh = *(const f32x4*)(shift + (size_t)mr0 * 6144 + col), sc = *(const f32x4*)(scale + (size_t)mr0 * 6144 + col); f32x4 y;
; #pragma unroll
;                 for (int e = 0; e < 4; ++e) y[e] = (v0[j][e] * rstd0 * gg[e]) * (1.f + sc[e]) + sh[e];
;                 u32x2 w; w.x = cvt_pk_bf16(y[0], y[1]); w.y = cvt_pk_bf16(y[2], y[3]); *(u32x2*)(dst + (size_t)row0 * DM + col) = w; }
;             if (has1) { const f32x4 sh = *(const f32x4*)(shift + (size_t)mr1 * 6144 + col), sc = *(const f32x4*)(scale + (size_t)mr1 * 6144 + col); f32x4 y;
; #pragma unroll
;                 for (int e = 0; e < 4; ++e) y[e] = (v1[j][e] * rstd1 * gg[e]) * (1.f + sc[e]) + sh[e];
;                 u32x2 w; w.x = cvt_pk_bf16(y[0], y[1]); w.y = cvt_pk_bf16(y[2], y[3]); *(u32x2*)(dst + (size_t)row1 * DM + col) = w; } }
.Lmn17_ni_6:
	s_add_u32 s14, s14, s1
	global_store_dwordx2 v123, v[114:115], s[22:23] offset:0 nt
	global_store_dwordx2 v123, v[116:117], s[22:23] offset:512 nt
	global_store_dwordx2 v123, v[118:119], s[22:23] offset:1024 nt
	global_store_dwordx2 v123, v[120:121], s[22:23] offset:1536 nt
	s_add_u32 s15, s15, s1
	s_cmp_ge_i32 s15, 0x8000
	s_cbranch_scc1 .Lmn17_done_1
	s_add_u32 s20, s15, s1
	s_cmp_ge_i32 s20, 0x8000
	s_cbranch_scc1 .Lmn17_wl_7
	s_waitcnt vmcnt(16)
	s_branch .Lmn17_wj_8

; DEV unsigned cvt_pk_bf16(float lo, float hi) { unsigned r; asm volatile("v_cvt_pk_bf16_f32 %0, %1, %2" : "=v"(r) : "v"(lo), "v"(hi)); return r; }
; DEV void modnorm_rows(const float* srcX, const float* srcC, int nrows, const float* g, const float* shift, const float* scale, bf16_t* dst, int gw, int NGW, int lane) {
;     ...
;         for (int j = 0; j < 4; ++j) { const int col = 256 * j + 4 * lane; const f32x4 gg = *(const f32x4*)(g + col);
;             { const f32x4 sh = *(const f32x4*)(shift + (size_t)mr0 * 6144 + col), sc = *(const f32x4*)(scale + (size_t)mr0 * 6144 + col); f32x4 y;
; #pragma unroll
;                 for (int e = 0; e < 4; ++e) y[e] = (v0[j][e] * rstd0 * gg[e]) * (1.f + sc[e]) + sh[e];
;                 u32x2 w; w.x = cvt_pk_bf16(y[0], y[1]); w.y = cvt_pk_bf16(y[2], y[3]); *(u32x2*)(dst + (size_t)row0 * DM + col) = w; }
;             if (has1) { const f32x4 sh = *(const f32x4*)(shift + (size_t)mr1 * 6144 + col), sc = *(const f32x4*)(scale + (size_t)mr1 * 6144 + col); f32x4 y;
; #pragma unroll
;                 for (int e = 0; e < 4; ++e) y[e] = (v1[j][e] * rstd1 * gg[e]) * (1.f + sc[e]) + sh[e];
;                 u32x2 w; w.x = cvt_pk_bf16(y[0], y[1]); w.y = cvt_pk_bf16(y[2], y[3]); *(u32x2*)(dst + (size_t)row1 * DM + col) = w; } }
.Lmn17_ni_13:
	s_add_u32 s14, s14, s1
	global_store_dwordx2 v123, v[114:115], s[22:23] offset:0 nt
	global_store_dwordx2 v123, v[116:117], s[22:23] offset:512 nt
	global_store_dwordx2 v123, v[118:119], s[22:23] offset:1024 nt
	global_store_dwordx2 v123, v[120:121], s[22:23] offset:1536 nt
	s_add_u32 s15, s15, s1
	s_cmp_ge_i32 s15, 0x8000
	s_cbranch_scc1 .Lmn17_done_1
	s_add_u32 s20, s15, s1
	s_cmp_ge_i32 s20, 0x8000
	s_cbranch_scc1 .Lmn17_wl_14
	s_waitcnt vmcnt(20)
	s_branch .Lmn17_wj_15
